# re-measure: diff attention exps/row sums inside P*V MFMA gaps
# baseline (speedup 1.0000x reference)
; DI bf16_t f2bf(float x) { return (bf16_t)(pk2(x, 0.f) & 0xffffu); }
; DI float bf2f(bf16_t v) { return __uint_as_float(((unsigned)v) << 16); }
; DI void hgrn_scan(const Params& p) {
;     ...
;   const int bh = gid >> 14, e = gid & 16383;
;   bf16_t* up = UT + (size_t)bh * 256 * 16384 + e;
;   const float* dp = dbuf + (size_t)bh * 256 * 128 + (e & 127);
;   float st = 0.f;
;   for (int c0 = 0; c0 < 256; c0 += 32) {
;     bf16_t u[32]; float dv[32];
; #pragma unroll
;     for (int i = 0; i < 32; ++i) { u[i] = up[(size_t)(c0 + i) * 16384]; dv[i] = dp[(size_t)(c0 + i) * 128]; }
; #pragma unroll
;     for (int i = 0; i < 32; ++i) {
;       up[(size_t)(c0 + i) * 16384] = f2bf(st);
;       st = dv[i] * st + bf2f(u[i]);
.LBB0_560:
	s_andn2_b64 vcc, exec, s[4:5]
	s_cbranch_vccnz .LBB0_585
	s_mov_b64 s[100:101], 0
.Lrep_s:
	s_mov_b64 s[4:5], s[74:75]
	s_load_dwordx4 s[8:11], s[4:5], 0xa8
	v_mov_b32_e32 v0, v192
	v_readlane_b32 s3, v254, 17
	s_waitcnt lgkmcnt(0)
	s_mov_b64 s[4:5], s[10:11]
	s_nop 0
	v_add_u32_e32 v2, s3, v0
	v_cmp_gt_i32_e32 vcc, s91, v2
	s_and_saveexec_b64 s[8:9], vcc
	s_cbranch_execz .LBB0_564
	v_ashrrev_i32_e32 v4, 14, v2
	v_ashrrev_i32_e32 v5, 31, v4
	v_and_b32_e32 v6, 0x3fff, v2
	v_lshlrev_b64 v[2:3], 23, v[4:5]
	v_lshlrev_b64 v[4:5], 17, v[4:5]
	v_and_b32_e32 v0, 0x7f, v0
	v_lshl_or_b32 v2, v6, 1, v2
	v_lshl_or_b32 v4, v0, 2, v4
	v_mov_b32_e32 v0, 0
	s_movk_i32 s3, 0xffe0
.LBB0_563:
	v_lshl_add_u64 v[8:9], s[10:11], 0, v[4:5]
	v_add_co_u32_e32 v10, vcc, 0x1e900000, v8
	v_lshl_add_u64 v[6:7], s[10:11], 0, v[2:3]
	s_nop 0
	v_addc_co_u32_e32 v11, vcc, 0, v9, vcc
	v_add_co_u32_e32 v12, vcc, 0x1e901000, v8
	global_load_dword v68, v[10:11], off
	global_load_dword v69, v[10:11], off offset:512
	global_load_dword v70, v[10:11], off offset:1024
	global_load_dword v71, v[10:11], off offset:1536
	global_load_dword v72, v[10:11], off offset:2048
	global_load_dword v73, v[10:11], off offset:2560
	global_load_dword v74, v[10:11], off offset:3072
	global_load_dword v75, v[10:11], off offset:3584
	v_addc_co_u32_e32 v13, vcc, 0, v9, vcc
	v_add_co_u32_e32 v10, vcc, 0x1e902000, v8
	global_load_dword v76, v[12:13], off
	global_load_dword v77, v[12:13], off offset:512
	global_load_dword v78, v[12:13], off offset:1024
	global_load_dword v79, v[12:13], off offset:1536
	global_load_dword v80, v[12:13], off offset:2048
	global_load_dword v81, v[12:13], off offset:2560
	global_load_dword v82, v[12:13], off offset:3072
	global_load_dword v83, v[12:13], off offset:3584
	v_addc_co_u32_e32 v11, vcc, 0, v9, vcc
	v_add_co_u32_e32 v8, vcc, 0x1e903000, v8
	global_load_dword v84, v[10:11], off
	global_load_dword v85, v[10:11], off offset:512
	global_load_dword v86, v[10:11], off offset:1024
	global_load_dword v87, v[10:11], off offset:1536
	global_load_dword v88, v[10:11], off offset:2048
	global_load_dword v89, v[10:11], off offset:2560
	global_load_dword v90, v[10:11], off offset:3072
	global_load_dword v91, v[10:11], off offset:3584
	v_addc_co_u32_e32 v9, vcc, 0, v9, vcc
	v_add_co_u32_e32 v26, vcc, 0x1a900000, v6
	global_load_dword v92, v[8:9], off
	global_load_dword v93, v[8:9], off offset:512
	global_load_dword v94, v[8:9], off offset:1024
	global_load_dword v95, v[8:9], off offset:1536
	global_load_dword v96, v[8:9], off offset:2048
	global_load_dword v97, v[8:9], off offset:2560
	global_load_dword v98, v[8:9], off offset:3072
	global_load_dword v99, v[8:9], off offset:3584
	v_addc_co_u32_e32 v27, vcc, 0, v7, vcc
	v_add_co_u32_e32 v8, vcc, 0x1a908000, v6
	v_cvt_pk_bf16_f32 v25, v0, s0
	s_nop 0
	v_addc_co_u32_e32 v9, vcc, 0, v7, vcc
	v_add_co_u32_e32 v10, vcc, 0x1a910000, v6
	global_load_ushort v100, v[26:27], off
	global_load_ushort v101, v[8:9], off
	v_addc_co_u32_e32 v11, vcc, 0, v7, vcc
	v_add_co_u32_e32 v18, vcc, 0x1a918000, v6
	s_mov_b64 s[12:13], 0x100000
	s_nop 0
	v_addc_co_u32_e32 v19, vcc, 0, v7, vcc
	v_add_co_u32_e32 v12, vcc, 0x1a920000, v6
	global_load_ushort v102, v[10:11], off
	global_load_ushort v103, v[18:19], off
	v_addc_co_u32_e32 v13, vcc, 0, v7, vcc
	v_add_co_u32_e32 v20, vcc, 0x1a928000, v6
	s_add_i32 s3, s3, 32
	s_nop 0
	v_addc_co_u32_e32 v21, vcc, 0, v7, vcc
	v_add_co_u32_e32 v14, vcc, 0x1a930000, v6
	global_load_ushort v104, v[12:13], off
	global_load_ushort v105, v[20:21], off
	v_addc_co_u32_e32 v15, vcc, 0, v7, vcc
	v_add_co_u32_e32 v22, vcc, 0x1a938000, v6
	v_lshl_add_u64 v[2:3], v[2:3], 0, s[12:13]
	s_nop 0
	v_addc_co_u32_e32 v23, vcc, 0, v7, vcc
	v_add_co_u32_e32 v16, vcc, 0x1a940000, v6
	global_load_ushort v106, v[14:15], off
	global_load_ushort v107, v[22:23], off
	v_addc_co_u32_e32 v17, vcc, 0, v7, vcc
	v_add_co_u32_e32 v24, vcc, 0x1a948000, v6
	s_mov_b64 exec, s[100:101]
	global_store_short v[26:27], v25, off
	s_mov_b64 exec, -1
	s_nop 0
	v_addc_co_u32_e32 v25, vcc, 0, v7, vcc
	v_add_co_u32_e32 v26, vcc, 0x1a950000, v6
	global_load_ushort v108, v[16:17], off
	global_load_ushort v109, v[24:25], off
	v_addc_co_u32_e32 v27, vcc, 0, v7, vcc
	v_add_co_u32_e32 v28, vcc, 0x1a958000, v6
	s_mov_b64 s[12:13], 0x4000
	s_nop 0
	v_addc_co_u32_e32 v29, vcc, 0, v7, vcc
	v_add_co_u32_e32 v30, vcc, 0x1a960000, v6
	global_load_ushort v110, v[26:27], off
	global_load_ushort v111, v[28:29], off
	v_addc_co_u32_e32 v31, vcc, 0, v7, vcc
	v_add_co_u32_e32 v32, vcc, 0x1a968000, v6
	v_lshl_add_u64 v[4:5], v[4:5], 0, s[12:13]
	s_nop 0
	v_addc_co_u32_e32 v33, vcc, 0, v7, vcc
	s_waitcnt vmcnt(50)
	v_add_co_u32_e32 v34, vcc, 0x1a970000, v6
	global_load_ushort v112, v[30:31], off
	global_load_ushort v113, v[32:33], off
	v_addc_co_u32_e32 v35, vcc, 0, v7, vcc
	v_add_co_u32_e32 v36, vcc, 0x1a978000, v6
	s_cmpk_lt_u32 s3, 0xe0
	s_nop 0
	v_addc_co_u32_e32 v37, vcc, 0, v7, vcc
	s_waitcnt vmcnt(51)
	v_add_co_u32_e32 v38, vcc, 0x1a980000, v6
	global_load_ushort v114, v[34:35], off
	global_load_ushort v115, v[36:37], off
	v_addc_co_u32_e32 v39, vcc, 0, v7, vcc
	v_add_co_u32_e32 v40, vcc, 0x1a988000, v6
	s_waitcnt vmcnt(16)
	v_lshlrev_b32_e32 v100, 16, v100
	v_addc_co_u32_e32 v41, vcc, 0, v7, vcc
	v_add_co_u32_e32 v42, vcc, 0x1a990000, v6
	global_load_ushort v116, v[38:39], off
	global_load_ushort v117, v[40:41], off
	v_addc_co_u32_e32 v43, vcc, 0, v7, vcc
	v_add_co_u32_e32 v44, vcc, 0x1a998000, v6
	v_fmac_f32_e32 v100, v0, v68
	s_nop 0
	v_addc_co_u32_e32 v45, vcc, 0, v7, vcc
	v_add_co_u32_e32 v46, vcc, 0x1a9a0000, v6
	global_load_ushort v118, v[42:43], off
	global_load_ushort v119, v[44:45], off
	v_addc_co_u32_e32 v47, vcc, 0, v7, vcc
	v_add_co_u32_e32 v48, vcc, 0x1a9a8000, v6
	s_waitcnt vmcnt(19)
; DI bf16_t f2bf(float x) { return (bf16_t)(pk2(x, 0.f) & 0xffffu); }
; DI float bf2f(bf16_t v) { return __uint_as_float(((unsigned)v) << 16); }
; DI void hgrn_scan(const Params& p) {
;     ...
;     bf16_t u[32]; float dv[32];
; #pragma unroll
;     for (int i = 0; i < 32; ++i) { u[i] = up[(size_t)(c0 + i) * 16384]; dv[i] = dp[(size_t)(c0 + i) * 128]; }
; #pragma unroll
;     for (int i = 0; i < 32; ++i) {
;       up[(size_t)(c0 + i) * 16384] = f2bf(st);
;       st = dv[i] * st + bf2f(u[i]);
;     }
	v_lshlrev_b32_e32 v0, 16, v101
	v_addc_co_u32_e32 v49, vcc, 0, v7, vcc
	v_add_co_u32_e32 v50, vcc, 0x1a9b0000, v6
	global_load_ushort v120, v[46:47], off
	global_load_ushort v121, v[48:49], off
	v_addc_co_u32_e32 v51, vcc, 0, v7, vcc
	v_add_co_u32_e32 v52, vcc, 0x1a9b8000, v6
	v_cvt_pk_bf16_f32 v68, v100, s0
	s_nop 0
	v_addc_co_u32_e32 v53, vcc, 0, v7, vcc
	v_add_co_u32_e32 v54, vcc, 0x1a9c0000, v6
	global_load_ushort v122, v[50:51], off
	global_load_ushort v123, v[52:53], off
	v_addc_co_u32_e32 v55, vcc, 0, v7, vcc
	v_add_co_u32_e32 v56, vcc, 0x1a9c8000, v6
	v_fmac_f32_e32 v0, v69, v100
	s_nop 0
	v_addc_co_u32_e32 v57, vcc, 0, v7, vcc
	v_add_co_u32_e32 v58, vcc, 0x1a9d0000, v6
	global_load_ushort v124, v[54:55], off
	global_load_ushort v125, v[56:57], off
	v_addc_co_u32_e32 v59, vcc, 0, v7, vcc
	v_add_co_u32_e32 v60, vcc, 0x1a9d8000, v6
	s_waitcnt vmcnt(24)
	v_lshlrev_b32_e32 v69, 16, v102
	v_addc_co_u32_e32 v61, vcc, 0, v7, vcc
	v_add_co_u32_e32 v62, vcc, 0x1a9e0000, v6
	global_load_ushort v126, v[58:59], off
	global_load_ushort v127, v[60:61], off
	v_addc_co_u32_e32 v63, vcc, 0, v7, vcc
	v_add_co_u32_e32 v64, vcc, 0x1a9e8000, v6
	v_fmac_f32_e32 v69, v70, v0
	s_nop 0
	v_addc_co_u32_e32 v65, vcc, 0, v7, vcc
	v_add_co_u32_e32 v66, vcc, 0x1a9f0000, v6
	global_load_ushort v128, v[62:63], off
	global_load_ushort v129, v[64:65], off
	v_addc_co_u32_e32 v67, vcc, 0, v7, vcc
	v_add_co_u32_e32 v6, vcc, 0x1a9f8000, v6
	s_nop 1
	v_addc_co_u32_e32 v7, vcc, 0, v7, vcc
	global_load_ushort v130, v[66:67], off
	global_load_ushort v131, v[6:7], off
	s_nop 0
	s_mov_b64 exec, s[100:101]
	global_store_short v[8:9], v68, off
	s_mov_b64 exec, -1
	v_cvt_pk_bf16_f32 v8, v0, s0
	s_waitcnt vmcnt(30)
	v_lshlrev_b32_e32 v0, 16, v103
	s_mov_b64 exec, s[100:101]
	global_store_short v[10:11], v8, off
	s_mov_b64 exec, -1
	v_cvt_pk_bf16_f32 v8, v69, s0
	v_fmac_f32_e32 v0, v71, v69
	s_waitcnt vmcnt(30)
	v_lshlrev_b32_e32 v9, 16, v104
	s_mov_b64 exec, s[100:101]
	global_store_short v[18:19], v8, off
	s_mov_b64 exec, -1
	v_cvt_pk_bf16_f32 v8, v0, s0
	v_fmac_f32_e32 v9, v72, v0
	s_waitcnt vmcnt(30)
	v_lshlrev_b32_e32 v0, 16, v105
	s_mov_b64 exec, s[100:101]
	global_store_short v[12:13], v8, off
	s_mov_b64 exec, -1
	v_cvt_pk_bf16_f32 v8, v9, s0
	v_fmac_f32_e32 v0, v73, v9
	s_waitcnt vmcnt(30)
	v_lshlrev_b32_e32 v9, 16, v106
	s_mov_b64 exec, s[100:101]
	global_store_short v[20:21], v8, off
	s_mov_b64 exec, -1
	v_cvt_pk_bf16_f32 v8, v0, s0
	v_fmac_f32_e32 v9, v74, v0
	s_waitcnt vmcnt(30)
	v_lshlrev_b32_e32 v0, 16, v107
	s_mov_b64 exec, s[100:101]
	global_store_short v[14:15], v8, off
	s_mov_b64 exec, -1
	v_cvt_pk_bf16_f32 v8, v9, s0
	v_fmac_f32_e32 v0, v75, v9
	s_waitcnt vmcnt(29)
	v_lshlrev_b32_e32 v9, 16, v108
	s_mov_b64 exec, s[100:101]
	global_store_short v[22:23], v8, off
	s_mov_b64 exec, -1
	v_cvt_pk_bf16_f32 v8, v0, s0
	v_fmac_f32_e32 v9, v76, v0
	s_waitcnt vmcnt(29)
	v_lshlrev_b32_e32 v0, 16, v109
	s_mov_b64 exec, s[100:101]
	global_store_short v[16:17], v8, off
	s_mov_b64 exec, -1
	v_cvt_pk_bf16_f32 v8, v9, s0
	v_fmac_f32_e32 v0, v77, v9
	s_waitcnt vmcnt(29)
	v_lshlrev_b32_e32 v9, 16, v110
	s_mov_b64 exec, s[100:101]
	global_store_short v[24:25], v8, off
	s_mov_b64 exec, -1
	v_cvt_pk_bf16_f32 v8, v0, s0
	v_fmac_f32_e32 v9, v78, v0
	s_waitcnt vmcnt(29)
	v_lshlrev_b32_e32 v0, 16, v111
	s_mov_b64 exec, s[100:101]
	global_store_short v[26:27], v8, off
	s_mov_b64 exec, -1
	v_cvt_pk_bf16_f32 v8, v9, s0
	v_fmac_f32_e32 v0, v79, v9
	s_waitcnt vmcnt(29)
	v_lshlrev_b32_e32 v9, 16, v112
	s_mov_b64 exec, s[100:101]
	global_store_short v[28:29], v8, off
	s_mov_b64 exec, -1
	v_cvt_pk_bf16_f32 v8, v0, s0
	v_fmac_f32_e32 v9, v80, v0
	s_waitcnt vmcnt(29)
	v_lshlrev_b32_e32 v0, 16, v113
	s_mov_b64 exec, s[100:101]
	global_store_short v[30:31], v8, off
	s_mov_b64 exec, -1
	v_cvt_pk_bf16_f32 v8, v9, s0
	v_fmac_f32_e32 v0, v81, v9
	s_waitcnt vmcnt(29)
	v_lshlrev_b32_e32 v9, 16, v114
	s_mov_b64 exec, s[100:101]
	global_store_short v[32:33], v8, off
	s_mov_b64 exec, -1
	v_cvt_pk_bf16_f32 v8, v0, s0
	v_fmac_f32_e32 v9, v82, v0
	s_waitcnt vmcnt(29)
	v_lshlrev_b32_e32 v0, 16, v115
	s_mov_b64 exec, s[100:101]
	global_store_short v[34:35], v8, off
	s_mov_b64 exec, -1
	v_cvt_pk_bf16_f32 v8, v9, s0
	v_fmac_f32_e32 v0, v83, v9
	s_waitcnt vmcnt(29)
; #define GAS __attribute__((address_space(1)))
; DI bf16_t f2bf(float x) { return (bf16_t)(pk2(x, 0.f) & 0xffffu); }
; DI float bf2f(bf16_t v) { return __uint_as_float(((unsigned)v) << 16); }
; DI void hgrn_scan(const Params& p) {
;     ...
;     for (int i = 0; i < 32; ++i) {
;       up[(size_t)(c0 + i) * 16384] = f2bf(st);
;       st = dv[i] * st + bf2f(u[i]);
;     }
;   }
; DI void grid_barrier(unsigned* ctr, const unsigned target) {
;   asm volatile("s_waitcnt vmcnt(0)" ::: "memory");
;   __syncthreads();
;   if (threadIdx.x == 0) {
;     __builtin_amdgcn_fence(__ATOMIC_RELEASE, "agent");
;     asm volatile("s_waitcnt vmcnt(0)" ::: "memory");
;     __hip_atomic_fetch_add((GAS unsigned*)ctr, 1u, __ATOMIC_RELAXED, __HIP_MEMORY_SCOPE_AGENT);
;     while (__hip_atomic_load((GAS unsigned*)ctr, __ATOMIC_RELAXED, __HIP_MEMORY_SCOPE_AGENT) < target) __builtin_amdgcn_s_sleep(1);
	v_lshlrev_b32_e32 v9, 16, v116
	s_mov_b64 exec, s[100:101]
	global_store_short v[36:37], v8, off
	s_mov_b64 exec, -1
	v_cvt_pk_bf16_f32 v8, v0, s0
	v_fmac_f32_e32 v9, v84, v0
	s_waitcnt vmcnt(29)
	v_lshlrev_b32_e32 v0, 16, v117
	s_mov_b64 exec, s[100:101]
	global_store_short v[38:39], v8, off
	s_mov_b64 exec, -1
	v_cvt_pk_bf16_f32 v8, v9, s0
	v_fmac_f32_e32 v0, v85, v9
	s_waitcnt vmcnt(29)
	v_lshlrev_b32_e32 v9, 16, v118
	s_mov_b64 exec, s[100:101]
	global_store_short v[40:41], v8, off
	s_mov_b64 exec, -1
	v_cvt_pk_bf16_f32 v8, v0, s0
	v_fmac_f32_e32 v9, v86, v0
	s_waitcnt vmcnt(29)
	v_lshlrev_b32_e32 v0, 16, v119
	s_mov_b64 exec, s[100:101]
	global_store_short v[42:43], v8, off
	s_mov_b64 exec, -1
	v_cvt_pk_bf16_f32 v8, v9, s0
	v_fmac_f32_e32 v0, v87, v9
	s_waitcnt vmcnt(29)
	v_lshlrev_b32_e32 v9, 16, v120
	s_mov_b64 exec, s[100:101]
	global_store_short v[44:45], v8, off
	s_mov_b64 exec, -1
	v_cvt_pk_bf16_f32 v8, v0, s0
	v_fmac_f32_e32 v9, v88, v0
	s_waitcnt vmcnt(29)
	v_lshlrev_b32_e32 v0, 16, v121
	s_mov_b64 exec, s[100:101]
	global_store_short v[46:47], v8, off
	s_mov_b64 exec, -1
	v_cvt_pk_bf16_f32 v8, v9, s0
	v_fmac_f32_e32 v0, v89, v9
	s_waitcnt vmcnt(29)
	v_lshlrev_b32_e32 v9, 16, v122
	s_mov_b64 exec, s[100:101]
	global_store_short v[48:49], v8, off
	s_mov_b64 exec, -1
	v_cvt_pk_bf16_f32 v8, v0, s0
	v_fmac_f32_e32 v9, v90, v0
	s_waitcnt vmcnt(29)
	v_lshlrev_b32_e32 v0, 16, v123
	s_mov_b64 exec, s[100:101]
	global_store_short v[50:51], v8, off
	s_mov_b64 exec, -1
	v_cvt_pk_bf16_f32 v8, v9, s0
	v_fmac_f32_e32 v0, v91, v9
	s_waitcnt vmcnt(29)
	v_lshlrev_b32_e32 v9, 16, v124
	s_mov_b64 exec, s[100:101]
	global_store_short v[52:53], v8, off
	s_mov_b64 exec, -1
	v_cvt_pk_bf16_f32 v8, v0, s0
	v_fmac_f32_e32 v9, v92, v0
	s_waitcnt vmcnt(29)
	v_lshlrev_b32_e32 v0, 16, v125
	s_mov_b64 exec, s[100:101]
	global_store_short v[54:55], v8, off
	s_mov_b64 exec, -1
	v_cvt_pk_bf16_f32 v8, v9, s0
	v_fmac_f32_e32 v0, v93, v9
	s_waitcnt vmcnt(29)
	v_lshlrev_b32_e32 v9, 16, v126
	s_mov_b64 exec, s[100:101]
	global_store_short v[56:57], v8, off
	s_mov_b64 exec, -1
	v_cvt_pk_bf16_f32 v8, v0, s0
	v_fmac_f32_e32 v9, v94, v0
	s_waitcnt vmcnt(29)
	v_lshlrev_b32_e32 v0, 16, v127
	s_mov_b64 exec, s[100:101]
	global_store_short v[58:59], v8, off
	s_mov_b64 exec, -1
	v_cvt_pk_bf16_f32 v8, v9, s0
	v_fmac_f32_e32 v0, v95, v9
	s_waitcnt vmcnt(29)
	v_lshlrev_b32_e32 v9, 16, v128
	s_mov_b64 exec, s[100:101]
	global_store_short v[60:61], v8, off
	s_mov_b64 exec, -1
	v_cvt_pk_bf16_f32 v8, v0, s0
	v_fmac_f32_e32 v9, v96, v0
	s_waitcnt vmcnt(29)
	v_lshlrev_b32_e32 v0, 16, v129
	s_mov_b64 exec, s[100:101]
	global_store_short v[62:63], v8, off
	s_mov_b64 exec, -1
	v_cvt_pk_bf16_f32 v8, v9, s0
	v_fmac_f32_e32 v0, v97, v9
	s_waitcnt vmcnt(29)
	v_lshlrev_b32_e32 v9, 16, v130
	s_mov_b64 exec, s[100:101]
	global_store_short v[64:65], v8, off
	s_mov_b64 exec, -1
	v_cvt_pk_bf16_f32 v8, v0, s0
	v_fmac_f32_e32 v9, v98, v0
	s_waitcnt vmcnt(29)
	v_lshlrev_b32_e32 v0, 16, v131
	s_mov_b64 exec, s[100:101]
	global_store_short v[66:67], v8, off
	s_mov_b64 exec, -1
	v_cvt_pk_bf16_f32 v8, v9, s0
	v_fmac_f32_e32 v0, v99, v9
	s_mov_b64 exec, s[100:101]
	global_store_short v[6:7], v8, off
	s_mov_b64 exec, -1
	s_cbranch_scc1 .LBB0_563
.LBB0_564:
	s_or_b64 exec, exec, s[8:9]
	s_waitcnt vmcnt(0) lgkmcnt(0)
	s_barrier
	s_cmp_eq_u32 s100, 0
	s_mov_b64 s[100:101], -1
	s_cbranch_scc1 .Lrep_s
	v_readlane_b32 s3, v254, 12
	s_add_i32 s16, s3, 3
	s_cmp_ge_i32 s16, s79
	s_cbranch_scc1 .LBB0_585
	s_cmp_lg_u32 s2, s78
	s_mov_b64 s[8:9], -1
	s_cbranch_scc0 .LBB0_573
	s_waitcnt vmcnt(0)
	s_waitcnt vmcnt(63) expcnt(7) lgkmcnt(15)
	s_barrier
	s_mov_b64 s[8:9], exec
	v_readlane_b32 s10, v254, 26
	v_readlane_b32 s11, v254, 27
	s_and_b64 s[10:11], s[8:9], s[10:11]
	s_mov_b64 exec, s[10:11]
	s_cbranch_execz .LBB0_572
	s_mov_b64 s[10:11], exec
	buffer_wbl2 sc1
	s_waitcnt vmcnt(0)
	s_waitcnt vmcnt(0)
	v_mbcnt_lo_u32_b32 v0, s10, 0
	s_add_u32 s4, s4, 0x1ee14400
	v_mbcnt_hi_u32_b32 v0, s11, v0
	s_addc_u32 s5, s5, 0
	v_cmp_eq_u32_e32 vcc, 0, v0
	s_and_saveexec_b64 s[12:13], vcc
	s_cbranch_execz .LBB0_569
	s_bcnt1_i32_b64 s3, s[10:11]
	v_mov_b32_e32 v0, s3
	global_atomic_add v1, v0, s[4:5]

; __global__ void __launch_bounds__(512) fwd_mega(Params p_arg) {
	.amdhsa_kernel _Z8fwd_mega6Params
		.amdhsa_group_segment_fixed_size 0
		.amdhsa_private_segment_fixed_size 0
		.amdhsa_kernarg_size 448
		.amdhsa_user_sgpr_count 2
		.amdhsa_user_sgpr_dispatch_ptr 0
		.amdhsa_user_sgpr_queue_ptr 0
		.amdhsa_user_sgpr_kernarg_segment_ptr 1
		.amdhsa_user_sgpr_dispatch_id 0
		.amdhsa_user_sgpr_kernarg_preload_length 0
		.amdhsa_user_sgpr_kernarg_preload_offset 0
		.amdhsa_user_sgpr_private_segment_size 0
		.amdhsa_uses_dynamic_stack 0
		.amdhsa_enable_private_segment 0
		.amdhsa_system_sgpr_workgroup_id_x 1
		.amdhsa_system_sgpr_workgroup_id_y 0
		.amdhsa_system_sgpr_workgroup_id_z 0
		.amdhsa_system_sgpr_workgroup_info 0
		.amdhsa_system_vgpr_workitem_id 2
		.amdhsa_next_free_vgpr 256
		.amdhsa_next_free_sgpr 102
		.amdhsa_accum_offset 256
		.amdhsa_reserve_vcc 1
		.amdhsa_float_round_mode_32 0
		.amdhsa_float_round_mode_16_64 0
		.amdhsa_float_denorm_mode_32 3
		.amdhsa_float_denorm_mode_16_64 3
		.amdhsa_dx10_clamp 1
		.amdhsa_ieee_mode 1
		.amdhsa_fp16_overflow 0
		.amdhsa_tg_split 0
		.amdhsa_exception_fp_ieee_invalid_op 0
		.amdhsa_exception_fp_denorm_src 0
		.amdhsa_exception_fp_ieee_div_zero 0
		.amdhsa_exception_fp_ieee_overflow 0
		.amdhsa_exception_fp_ieee_underflow 0
		.amdhsa_exception_fp_ieee_inexact 0
		.amdhsa_exception_int_div_zero 0
	.end_amdhsa_kernel

; __global__ void __launch_bounds__(512) fwd_mega(Params p_arg) {
amdhsa.kernels:
  - .agpr_count:     0
    .args:
      - .offset:         0
        .size:           192
        .value_kind:     by_value
      - .offset:         192
        .size:           4
        .value_kind:     hidden_block_count_x
      - .offset:         196
        .size:           4
        .value_kind:     hidden_block_count_y
      - .offset:         200
        .size:           4
        .value_kind:     hidden_block_count_z
      - .offset:         204
        .size:           2
        .value_kind:     hidden_group_size_x
      - .offset:         206
        .size:           2
        .value_kind:     hidden_group_size_y
      - .offset:         208
        .size:           2
        .value_kind:     hidden_group_size_z
      - .offset:         210
        .size:           2
        .value_kind:     hidden_remainder_x
      - .offset:         212
        .size:           2
        .value_kind:     hidden_remainder_y
      - .offset:         214
        .size:           2
        .value_kind:     hidden_remainder_z
      - .offset:         232
        .size:           8
        .value_kind:     hidden_global_offset_x
      - .offset:         240
        .size:           8
        .value_kind:     hidden_global_offset_y
      - .offset:         248
        .size:           8
        .value_kind:     hidden_global_offset_z
      - .offset:         256
        .size:           2
        .value_kind:     hidden_grid_dims
      - .offset:         280
        .size:           8
        .value_kind:     hidden_multigrid_sync_arg
      - .offset:         312
        .size:           4
        .value_kind:     hidden_dynamic_lds_size
    .group_segment_fixed_size: 0
    .kernarg_segment_align: 8
    .kernarg_segment_size: 448
    .language:       OpenCL C
    .language_version:
      - 2
      - 0
    .max_flat_workgroup_size: 512
    .name:           _Z8fwd_mega6Params
    .private_segment_fixed_size: 0
    .sgpr_count:     108
    .sgpr_spill_count: 92
    .symbol:         _Z8fwd_mega6Params.kd
    .uniform_work_group_size: 1
    .uses_dynamic_stack: false
    .vgpr_count:     256
    .vgpr_spill_count: 0
    .wavefront_size: 64
